# v20 + next K tile written to LDS right after the last PV MFMA
# baseline (speedup 1.0000x reference)
; __device__ __forceinline__ void finishSM(f32x16& p0, f32x16& p1, float alpha, float& l_reg, bf16x8& pa0, bf16x8& pa1, bf16x8& pa2, bf16x8& pa3) {
;     for (int r = 0; r < 16; ++r) p1[r] = __builtin_amdgcn_exp2f(p1[r]);
;     float ps = 0; for (int r = 0; r < 16; ++r) ps += p0[r]; for (int r = 0; r < 16; ++r) ps += p1[r];
;     { auto rr = __builtin_amdgcn_permlane32_swap(__float_as_uint(ps), __float_as_uint(ps), false, false);
;       ps = __uint_as_float(rr[0]) + __uint_as_float(rr[1]); }
;     l_reg = l_reg * alpha + ps;
;     ...
;     PK4(p0, 0, pa0); PK4(p0, 8, pa1); PK4(p1, 0, pa2); PK4(p1, 8, pa3);
;     ...
; }
; template <int KB>
; __device__ __forceinline__ void qkt(f32x16& p0, f32x16& p1, const char* K_lds, int r32, int hi, const bf16x8* qr) {
;     p0 = f32x16{}; p1 = f32x16{};
;     const char* kb[4];
; #pragma unroll
;     for (int dd = 0; dd < 4; ++dd) kb[dd] = K_lds + KB * SHM_K + KSWZ(r32, (dd * 16 + hi * 8) * 2);
; #pragma unroll
;     for (int d0 = 0; d0 < 8; ++d0) { const char* a = kb[d0 & 3] + (d0 >> 2) * 128;
;         bf16x8 b0 = *reinterpret_cast<const bf16x8*>(a);
;         bf16x8 b1 = *reinterpret_cast<const bf16x8*>(a + 32 * 256);
;         p0 = __builtin_amdgcn_mfma_f32_32x32x16_bf16(b0, qr[d0], p0, 0, 0, 0);
;         p1 = __builtin_amdgcn_mfma_f32_32x32x16_bf16(b1, qr[d0], p1, 0, 0, 0); }
.Lmy_hs1_nov:
	s_mov_b32 s100, 0
	ds_read_b128 v[66:69], v169 offset:49152
	ds_read_b128 v[70:73], v169 offset:57344
	ds_read_b128 v[100:103], v193 offset:49152
	ds_read_b128 v[136:139], v193 offset:57344
	s_waitcnt lgkmcnt(3)
	v_mfma_f32_32x32x16_bf16 v[82:97], v[66:69], v[132:135], 0
	v_add_f32_e32 v148, 0, v231
	v_add_f32_e32 v148, v233, v148
	v_add_f32_e32 v148, v229, v148
	v_add_f32_e32 v148, v232, v148
	v_add_f32_e32 v148, v228, v148
	s_waitcnt lgkmcnt(2)
	v_mfma_f32_32x32x16_bf16 v[66:81], v[70:73], v[132:135], 0
	v_add_f32_e32 v148, v230, v148
	v_add_f32_e32 v148, v226, v148
	v_add_f32_e32 v148, v227, v148
	v_add_f32_e32 v148, v223, v148
	v_add_f32_e32 v148, v225, v148
	s_waitcnt lgkmcnt(1)
	v_mfma_f32_32x32x16_bf16 v[82:97], v[100:103], v[128:131], v[82:97]
	v_add_f32_e32 v148, v209, v148
	v_add_f32_e32 v148, v224, v148
	v_add_f32_e32 v148, v206, v148
	v_add_f32_e32 v148, v208, v148
	v_add_f32_e32 v148, v205, v148
	s_waitcnt lgkmcnt(0)
	v_mfma_f32_32x32x16_bf16 v[66:81], v[136:139], v[128:131], v[66:81]
	v_add_f32_e32 v148, v207, v148
	v_exp_f32_e32 v140, v152
	v_exp_f32_e32 v141, v153
	v_exp_f32_e32 v142, v180
	v_exp_f32_e32 v143, v181
	ds_read_b128 v[100:103], v194 offset:49152
	ds_read_b128 v[136:139], v194 offset:57344
	s_waitcnt lgkmcnt(1)
	v_mfma_f32_32x32x16_bf16 v[82:97], v[100:103], v[124:127], v[82:97]
	v_exp_f32_e32 v144, v160
	v_exp_f32_e32 v145, v161
	v_exp_f32_e32 v146, v154
	v_exp_f32_e32 v147, v155
	v_exp_f32_e32 v178, v178
	s_waitcnt lgkmcnt(0)
	v_mfma_f32_32x32x16_bf16 v[66:81], v[136:139], v[124:127], v[66:81]
	v_exp_f32_e32 v179, v179
	v_exp_f32_e32 v162, v162
	v_exp_f32_e32 v163, v163
	v_add_f32_e32 v148, v178, v148
	v_add_f32_e32 v148, v179, v148
	ds_read_b128 v[100:103], v195 offset:49152
	ds_read_b128 v[136:139], v195 offset:57344
	s_waitcnt lgkmcnt(1)
	v_mfma_f32_32x32x16_bf16 v[82:97], v[100:103], v[120:123], v[82:97]
	v_add_f32_e32 v148, v162, v148
	v_exp_f32_e32 v158, v158
	v_exp_f32_e32 v159, v159
	v_exp_f32_e32 v156, v156
	v_exp_f32_e32 v157, v157
	s_waitcnt lgkmcnt(0)
	v_mfma_f32_32x32x16_bf16 v[66:81], v[136:139], v[120:123], v[66:81]
	v_add_f32_e32 v148, v163, v148
	v_add_f32_e32 v148, v158, v148
	v_add_f32_e32 v148, v159, v148
	v_add_f32_e32 v148, v156, v148
	v_add_f32_e32 v148, v157, v148
	ds_read_b128 v[100:103], v169 offset:49280
	ds_read_b128 v[136:139], v169 offset:57472
	s_waitcnt lgkmcnt(1)
	v_mfma_f32_32x32x16_bf16 v[82:97], v[100:103], v[116:119], v[82:97]
	v_add_f32_e32 v148, v140, v148
	v_add_f32_e32 v148, v141, v148
	v_add_f32_e32 v148, v142, v148
	v_add_f32_e32 v148, v143, v148
	v_add_f32_e32 v148, v144, v148
	s_waitcnt lgkmcnt(0)
	v_mfma_f32_32x32x16_bf16 v[66:81], v[136:139], v[116:119], v[66:81]
	v_add_f32_e32 v148, v145, v148
	v_add_f32_e32 v148, v146, v148
	v_add_f32_e32 v199, v147, v148
	v_mov_b32_e32 v200, v199
	s_nop 1
	v_permlane32_swap_b32_e32 v199, v200
	v_cvt_pk_bf16_f32 v148, v231, v233
	ds_read_b128 v[100:103], v193 offset:49280
	ds_read_b128 v[136:139], v193 offset:57472
	s_waitcnt lgkmcnt(1)
	v_mfma_f32_32x32x16_bf16 v[82:97], v[100:103], v[112:115], v[82:97]
	v_cvt_pk_bf16_f32 v149, v229, v232
	v_cvt_pk_bf16_f32 v150, v228, v230
	v_cvt_pk_bf16_f32 v151, v226, v227
	v_cvt_pk_bf16_f32 v152, v223, v225
	v_cvt_pk_bf16_f32 v153, v209, v224
	s_waitcnt lgkmcnt(0)
	v_mfma_f32_32x32x16_bf16 v[66:81], v[136:139], v[112:115], v[66:81]
	v_cvt_pk_bf16_f32 v154, v206, v208
	v_cvt_pk_bf16_f32 v155, v205, v207
	v_cvt_pk_bf16_f32 v158, v158, v159
	v_cvt_pk_bf16_f32 v159, v156, v157
	v_cvt_pk_bf16_f32 v156, v178, v179
	ds_read_b128 v[100:103], v194 offset:49280
	ds_read_b128 v[136:139], v194 offset:57472
	s_waitcnt lgkmcnt(1)
	v_mfma_f32_32x32x16_bf16 v[82:97], v[100:103], v[108:111], v[82:97]
	v_cvt_pk_bf16_f32 v157, v162, v163
	v_cvt_pk_bf16_f32 v160, v140, v141
	v_cvt_pk_bf16_f32 v161, v142, v143
	v_cvt_pk_bf16_f32 v162, v144, v145
	v_cvt_pk_bf16_f32 v163, v146, v147
	s_waitcnt lgkmcnt(0)
	v_mfma_f32_32x32x16_bf16 v[66:81], v[136:139], v[108:111], v[66:81]
	s_nop 0
	v_permlane32_swap_b32_e32 v148, v150
	v_permlane32_swap_b32_e32 v149, v151
	v_permlane32_swap_b32_e32 v152, v154
	v_permlane32_swap_b32_e32 v153, v155
	ds_read_b128 v[100:103], v195 offset:49280
	ds_read_b128 v[136:139], v195 offset:57472
	s_waitcnt lgkmcnt(1)
	v_mfma_f32_32x32x16_bf16 v[82:97], v[100:103], v[104:107], v[82:97]
	v_permlane32_swap_b32_e32 v156, v158
	v_permlane32_swap_b32_e32 v157, v159
	v_permlane32_swap_b32_e32 v160, v162
	v_permlane32_swap_b32_e32 v161, v163
	s_waitcnt lgkmcnt(0)
	v_mfma_f32_32x32x16_bf16 v[66:81], v[136:139], v[104:107], v[66:81]
	v_add_u32_e32 v178, s7, v166
	v_add_u32_e32 v100, 1, v178
	v_add_u32_e32 v102, 33, v178
	v_ashrrev_i32_e32 v101, 31, v100
	v_ashrrev_i32_e32 v103, 31, v102
	v_lshlrev_b64 v[140:141], 8, v[100:101]
	v_lshlrev_b64 v[142:143], 8, v[102:103]
	v_lshl_add_u64 v[100:101], v[170:171], 0, v[140:141]
	v_lshl_add_u64 v[136:137], v[170:171], 0, v[142:143]
	v_lshl_add_u64 v[140:141], v[176:177], 0, v[140:141]
	v_lshl_add_u64 v[144:145], v[176:177], 0, v[142:143]
	global_load_dwordx4 v[100:103], v[100:101], off
	s_nop 0
	global_load_dwordx4 v[136:139], v[136:137], off
	s_nop 0
	global_load_dwordx4 v[140:143], v[140:141], off
	s_nop 0
	global_load_dwordx4 v[144:147], v[144:145], off
	ds_read_b64_tr_b16 v[172:173], v185 offset:0
	ds_read_b64_tr_b16 v[174:175], v185 offset:0x800
	ds_read_b64_tr_b16 v[202:203], v185 offset:0x1000
	ds_read_b64_tr_b16 v[204:205], v185 offset:0x1800
	ds_read_b64_tr_b16 v[206:207], v185 offset:0x2000
	ds_read_b64_tr_b16 v[208:209], v185 offset:0x2800
	ds_read_b64_tr_b16 v[224:225], v185 offset:0x3000
	ds_read_b64_tr_b16 v[226:227], v185 offset:0x3800
	s_waitcnt lgkmcnt(0)
; template <int VB>
; __device__ __forceinline__ void pv_tile(f32x16* o, int vb0, bf16x8 pa0, bf16x8 pa1, bf16x8 pa2, bf16x8 pa3) {
;     ...
;     PV_D0(0); PV_D0(1); PV_D0(2); PV_D0(3);
	s_nop 0
	v_mfma_f32_32x32x16_bf16 v[50:65], v[148:151], v[172:175], v[50:65]
	ds_read_b64_tr_b16 v[172:173], v185 offset:0x200
	ds_read_b64_tr_b16 v[174:175], v185 offset:0xa00
	v_mfma_f32_32x32x16_bf16 v[50:65], v[152:155], v[202:205], v[50:65]
	ds_read_b64_tr_b16 v[202:203], v185 offset:0x1200
	ds_read_b64_tr_b16 v[204:205], v185 offset:0x1a00
	v_mfma_f32_32x32x16_bf16 v[50:65], v[156:159], v[206:209], v[50:65]
	ds_read_b64_tr_b16 v[206:207], v185 offset:0x2200
	ds_read_b64_tr_b16 v[208:209], v185 offset:0x2a00
	v_mfma_f32_32x32x16_bf16 v[50:65], v[160:163], v[224:227], v[50:65]
	ds_read_b64_tr_b16 v[224:225], v185 offset:0x3200
	ds_read_b64_tr_b16 v[226:227], v185 offset:0x3a00
	s_waitcnt lgkmcnt(0)
	v_mfma_f32_32x32x16_bf16 v[34:49], v[148:151], v[172:175], v[34:49]
	ds_read_b64_tr_b16 v[172:173], v185 offset:0x400
	ds_read_b64_tr_b16 v[174:175], v185 offset:0xc00
	v_mfma_f32_32x32x16_bf16 v[34:49], v[152:155], v[202:205], v[34:49]
	ds_read_b64_tr_b16 v[202:203], v185 offset:0x1400
	ds_read_b64_tr_b16 v[204:205], v185 offset:0x1c00
	v_mfma_f32_32x32x16_bf16 v[34:49], v[156:159], v[206:209], v[34:49]
	ds_read_b64_tr_b16 v[206:207], v185 offset:0x2400
	ds_read_b64_tr_b16 v[208:209], v185 offset:0x2c00
	v_mfma_f32_32x32x16_bf16 v[34:49], v[160:163], v[224:227], v[34:49]
	ds_read_b64_tr_b16 v[224:225], v185 offset:0x3400
	ds_read_b64_tr_b16 v[226:227], v185 offset:0x3c00
	s_waitcnt lgkmcnt(0)
	v_mfma_f32_32x32x16_bf16 v[18:33], v[148:151], v[172:175], v[18:33]
	ds_read_b64_tr_b16 v[172:173], v185 offset:0x600
	ds_read_b64_tr_b16 v[174:175], v185 offset:0xe00
	v_mfma_f32_32x32x16_bf16 v[18:33], v[152:155], v[202:205], v[18:33]
	ds_read_b64_tr_b16 v[202:203], v185 offset:0x1600
	ds_read_b64_tr_b16 v[204:205], v185 offset:0x1e00
	v_mfma_f32_32x32x16_bf16 v[18:33], v[156:159], v[206:209], v[18:33]
	ds_read_b64_tr_b16 v[206:207], v185 offset:0x2600
	ds_read_b64_tr_b16 v[208:209], v185 offset:0x2e00
	v_mfma_f32_32x32x16_bf16 v[18:33], v[160:163], v[224:227], v[18:33]
	ds_read_b64_tr_b16 v[224:225], v185 offset:0x3600
	ds_read_b64_tr_b16 v[226:227], v185 offset:0x3e00
	s_waitcnt lgkmcnt(0)
	v_mfma_f32_32x32x16_bf16 v[2:17], v[148:151], v[172:175], v[2:17]
	s_cmp_le_i32 s7, s6
	v_mfma_f32_32x32x16_bf16 v[2:17], v[152:155], v[202:205], v[2:17]
	v_mfma_f32_32x32x16_bf16 v[2:17], v[156:159], v[206:209], v[2:17]
	v_mfma_f32_32x32x16_bf16 v[2:17], v[160:163], v[224:227], v[2:17]
	s_waitcnt vmcnt(1)
	ds_write_b128 v188, v[140:143] offset:32768
	s_waitcnt vmcnt(0)
	ds_write_b128 v188, v[144:147] offset:40960
	s_cbranch_scc1 .LBB0_91
	v_add_u32_e32 v148, 0x4000007b, v197
	v_cmp_gt_u32_e32 vcc, 2.0, v148
	v_add_u32_e32 v148, 0x5b, v197
	s_nop 0
	v_cndmask_b32_e32 v82, v220, v82, vcc
	v_cmp_lt_u32_e32 vcc, s33, v148
	v_add_u32_e32 v148, 0x7a, v197
	s_nop 0
	v_cndmask_b32_e32 v66, v220, v66, vcc
	v_cmp_lt_u32_e32 vcc, s33, v148
	v_add_u32_e32 v148, 0x5a, v197
	s_nop 0
	v_cndmask_b32_e32 v83, v220, v83, vcc
	v_cmp_lt_u32_e32 vcc, s33, v148
	v_add_u32_e32 v148, 0x79, v197
	s_nop 0
	v_cndmask_b32_e32 v67, v220, v67, vcc
	v_cmp_lt_u32_e32 vcc, s33, v148
	v_add_u32_e32 v148, 0x59, v197
	s_nop 0
	v_cndmask_b32_e32 v84, v220, v84, vcc
	v_cmp_lt_u32_e32 vcc, s33, v148
	v_add_u32_e32 v148, 0x78, v197
	s_nop 0
	v_cndmask_b32_e32 v68, v220, v68, vcc
	v_cmp_lt_u32_e32 vcc, s33, v148
	v_add_u32_e32 v148, 0x58, v197
	s_nop 0
	v_cndmask_b32_e32 v85, v220, v85, vcc
	v_cmp_lt_u32_e32 vcc, s33, v148
	v_add_u32_e32 v148, 0x73, v197
	s_nop 0
	v_cndmask_b32_e32 v69, v220, v69, vcc
	v_cmp_lt_u32_e32 vcc, s33, v148
	v_add_u32_e32 v148, 0x53, v197
	s_nop 0
	v_cndmask_b32_e32 v86, v220, v86, vcc
	v_cmp_lt_u32_e32 vcc, s33, v148
	v_add_u32_e32 v148, 0x72, v197
	s_nop 0
	v_cndmask_b32_e32 v70, v220, v70, vcc
	v_cmp_lt_u32_e32 vcc, s33, v148
	v_add_u32_e32 v148, 0x52, v197
	s_nop 0
	v_cndmask_b32_e32 v87, v220, v87, vcc
	v_cmp_lt_u32_e32 vcc, s33, v148
	v_add_u32_e32 v148, 0x71, v197
	s_nop 0
	v_cndmask_b32_e32 v71, v220, v71, vcc
	v_cmp_lt_u32_e32 vcc, s33, v148
	v_add_u32_e32 v148, 0x51, v197
	s_nop 0
	v_cndmask_b32_e32 v88, v220, v88, vcc
	v_cmp_lt_u32_e32 vcc, s33, v148
	v_add_u32_e32 v148, 0x70, v197
	s_nop 0
	v_cndmask_b32_e32 v72, v220, v72, vcc
	v_cmp_lt_u32_e32 vcc, s33, v148
	v_add_u32_e32 v148, 0x50, v197
	s_nop 0
	v_cndmask_b32_e32 v89, v220, v89, vcc
	v_cmp_lt_u32_e32 vcc, s33, v148
	v_add_u32_e32 v148, 0x6b, v197
	s_nop 0
	v_cndmask_b32_e32 v73, v220, v73, vcc
	v_cmp_lt_u32_e32 vcc, s33, v148
	v_add_u32_e32 v148, 0x4b, v197
	s_nop 0
	v_cndmask_b32_e32 v90, v220, v90, vcc
	v_cmp_lt_u32_e32 vcc, s33, v148
	v_add_u32_e32 v148, 0x6a, v197
	s_nop 0
	v_cndmask_b32_e32 v74, v220, v74, vcc
	v_cmp_lt_u32_e32 vcc, s33, v148
	v_add_u32_e32 v148, 0x4a, v197
	s_nop 0
	v_cndmask_b32_e32 v91, v220, v91, vcc
	v_cmp_lt_u32_e32 vcc, s33, v148
	v_add_u32_e32 v148, 0x69, v197
	s_nop 0
	v_cndmask_b32_e32 v75, v220, v75, vcc
	v_cmp_lt_u32_e32 vcc, s33, v148
	v_add_u32_e32 v148, 0x49, v197
	s_nop 0
	v_cndmask_b32_e32 v92, v220, v92, vcc
	v_cmp_lt_u32_e32 vcc, s33, v148
	v_add_u32_e32 v148, 0x68, v197
	s_nop 0
	v_cndmask_b32_e32 v76, v220, v76, vcc
	v_cmp_lt_u32_e32 vcc, s33, v148
	v_add_u32_e32 v148, 0x48, v197
	s_nop 0
	v_cndmask_b32_e32 v93, v220, v93, vcc
	v_cmp_lt_u32_e32 vcc, s33, v148
	v_add_u32_e32 v148, 0x63, v197
	s_nop 0
	v_cndmask_b32_e32 v77, v220, v77, vcc
	v_cmp_lt_u32_e32 vcc, s33, v148
	v_add_u32_e32 v148, 0x43, v197
	s_nop 0
	v_cndmask_b32_e32 v94, v220, v94, vcc
	v_cmp_lt_u32_e32 vcc, s33, v148
	v_add_u32_e32 v148, 0x62, v197
	s_nop 0
	v_cndmask_b32_e32 v78, v220, v78, vcc
	v_cmp_lt_u32_e32 vcc, s33, v148
	v_add_u32_e32 v148, 0x42, v197
	s_nop 0
	v_cndmask_b32_e32 v95, v220, v95, vcc
	v_cmp_lt_u32_e32 vcc, s33, v148
	v_add_u32_e32 v148, 0x61, v197
	s_nop 0
	v_cndmask_b32_e32 v79, v220, v79, vcc
	v_cmp_lt_u32_e32 vcc, s33, v148
	v_add_u32_e32 v148, 0x41, v197
	s_nop 0
	v_cndmask_b32_e32 v96, v220, v96, vcc
	v_cmp_lt_u32_e32 vcc, s33, v148
	v_add_u32_e32 v148, 0x60, v197
	s_nop 0
	v_cndmask_b32_e32 v80, v220, v80, vcc
	v_cmp_lt_u32_e32 vcc, s33, v148
	v_add_u32_e32 v148, 64, v197
	s_nop 0
	v_cndmask_b32_e32 v97, v220, v97, vcc
	v_cmp_lt_u32_e32 vcc, s33, v148
	s_nop 1
	v_cndmask_b32_e32 v81, v220, v81, vcc
; __device__ __forceinline__ void partialSM(f32x16& p0, f32x16& p1, float& m_reg, float& mn, float& alpha, bool rs) {
;     float pmax = p0[0]; for (int r = 1; r < 16; ++r) pmax = fmaxf(pmax, p0[r]); for (int r = 0; r < 16; ++r) pmax = fmaxf(pmax, p1[r]);
;     if (!rs) pmax = -__builtin_inff();
;     { auto rr = __builtin_amdgcn_permlane32_swap(__float_as_uint(pmax), __float_as_uint(pmax), false, false);
;       pmax = fmaxf(__uint_as_float(rr[0]), __uint_as_float(rr[1])); }
;     constexpr float C2 = 1.4426950408889634f * SCALE;
;     if (__builtin_expect(__all((pmax - m_reg) * SCALE <= THR), 1)) { mn = m_reg; alpha = 1.f; }
;     else { mn = fmaxf(m_reg, pmax); alpha = __builtin_amdgcn_exp2f((m_reg - mn) * C2); m_reg = mn; }
;     const float mnL = rs ? -mn * C2 : -__builtin_inff();
;     for (int r = 0; r < 16; ++r) p0[r] = fmaf(p0[r], C2, mnL); for (int r = 0; r < 16; ++r) p1[r] = fmaf(p1[r], C2, mnL);
;     for (int r = 0; r < 16; ++r) p0[r] = __builtin_amdgcn_exp2f(p0[r]);
; }
.LBB0_91:
	s_add_i32 s0, s3, -2
	s_lshr_b32 s8, s0, 2
	s_cmp_ge_i32 s8, s44
	s_cselect_b64 s[0:1], -1, 0
	s_lshl_b32 s8, 1, s8
	v_and_b32_e32 v148, s8, v165
	v_cmp_ne_u32_e32 vcc, 0, v148
	v_max_f32_e32 v148, v83, v83
	v_max_f32_e32 v149, v82, v82
	v_max_f32_e32 v148, v149, v148
	v_max3_f32 v148, v148, v84, v85
	v_max3_f32 v148, v148, v86, v87
	v_max3_f32 v148, v148, v88, v89
	v_max3_f32 v148, v148, v90, v91
	v_max3_f32 v148, v148, v92, v93
	v_max3_f32 v148, v148, v94, v95
	v_max3_f32 v148, v148, v96, v97
	v_max3_f32 v148, v148, v66, v67
	v_max3_f32 v148, v148, v68, v69
	v_max3_f32 v148, v148, v70, v71
	v_max3_f32 v148, v148, v72, v73
	v_max3_f32 v148, v148, v74, v75
	v_max3_f32 v148, v148, v76, v77
	v_max3_f32 v148, v148, v78, v79
	s_or_b64 s[40:41], s[0:1], vcc
	v_max3_f32 v148, v148, v80, v81
	v_cndmask_b32_e64 v148, v220, v148, s[40:41]
	v_mov_b32_e32 v149, v148
	s_nop 1
	v_permlane32_swap_b32_e32 v148, v149
	v_max_f32_e32 v149, v149, v149
	v_max_f32_e32 v148, v148, v148
	v_max_f32_e32 v148, v148, v149
	v_sub_f32_e32 v149, v148, v198
	v_mul_f32_e32 v149, 0x3db504f3, v149
	v_cmp_ge_f32_e32 vcc, s91, v149
	v_max_f32_e32 v149, v198, v198
	v_max_f32_e32 v148, v149, v148
	v_sub_f32_e32 v149, v198, v148
	v_mul_f32_e32 v149, 0x3e0293ee, v149
	v_exp_f32_e32 v149, v149
	s_cmp_eq_u64 vcc, exec
	s_cselect_b64 s[42:43], -1, 0
	s_waitcnt vmcnt(0)
	v_cndmask_b32_e64 v202, v149, 1.0, s[42:43]
	v_cmp_gt_f32_e32 vcc, 1.0, v202
	s_cbranch_vccz .LBB0_95
	s_and_saveexec_b64 s[0:1], s[38:39]
	ds_write_b32 v187, v202 offset:128
	s_or_b64 exec, exec, s[0:1]
	s_waitcnt lgkmcnt(0)
	ds_read_b128 v[150:153], v186 offset:224
	ds_read_b128 v[154:157], v186 offset:192
	ds_read_b128 v[158:161], v186 offset:160
	ds_read_b128 v[172:175], v186 offset:128
	s_waitcnt lgkmcnt(3)
	v_pk_mul_f32 v[64:65], v[64:65], v[152:153]
	s_waitcnt lgkmcnt(2)
	v_pk_mul_f32 v[60:61], v[60:61], v[156:157]
	s_waitcnt lgkmcnt(1)
	v_pk_mul_f32 v[56:57], v[56:57], v[160:161]
	s_waitcnt lgkmcnt(0)
	v_pk_mul_f32 v[52:53], v[52:53], v[174:175]
	v_pk_mul_f32 v[62:63], v[62:63], v[150:151]
	v_pk_mul_f32 v[58:59], v[58:59], v[154:155]
	v_pk_mul_f32 v[54:55], v[54:55], v[158:159]
	v_pk_mul_f32 v[50:51], v[50:51], v[172:173]
	v_pk_mul_f32 v[48:49], v[48:49], v[152:153]
	v_pk_mul_f32 v[44:45], v[44:45], v[156:157]
	v_pk_mul_f32 v[40:41], v[40:41], v[160:161]
	v_pk_mul_f32 v[36:37], v[36:37], v[174:175]
	v_pk_mul_f32 v[46:47], v[46:47], v[150:151]
	v_pk_mul_f32 v[42:43], v[42:43], v[154:155]
	v_pk_mul_f32 v[38:39], v[38:39], v[158:159]
	v_pk_mul_f32 v[34:35], v[34:35], v[172:173]
	v_pk_mul_f32 v[32:33], v[32:33], v[152:153]
	v_pk_mul_f32 v[28:29], v[28:29], v[156:157]
	v_pk_mul_f32 v[24:25], v[24:25], v[160:161]
	v_pk_mul_f32 v[20:21], v[20:21], v[174:175]
	v_pk_mul_f32 v[30:31], v[30:31], v[150:151]
	v_pk_mul_f32 v[26:27], v[26:27], v[154:155]
	v_pk_mul_f32 v[22:23], v[22:23], v[158:159]
	v_pk_mul_f32 v[18:19], v[18:19], v[172:173]
	v_pk_mul_f32 v[16:17], v[16:17], v[152:153]
	v_pk_mul_f32 v[12:13], v[12:13], v[156:157]
	v_pk_mul_f32 v[8:9], v[8:9], v[160:161]
	v_pk_mul_f32 v[4:5], v[4:5], v[174:175]
	v_pk_mul_f32 v[14:15], v[14:15], v[150:151]
	v_pk_mul_f32 v[10:11], v[10:11], v[154:155]
	v_pk_mul_f32 v[6:7], v[6:7], v[158:159]
	v_pk_mul_f32 v[2:3], v[2:3], v[172:173]

; __device__ __forceinline__ void mask_tile(f32x16& p0, f32x16& p1, int dq, unsigned W) {
;     const float NEG = -__builtin_inff();
; #pragma unroll
;     for (int r = 0; r < 16; ++r) {
;         const int c = (r & 3) + 8 * (r >> 2);
;         if ((unsigned)(dq - c) >= W) p0[r] = NEG;
;         if ((unsigned)(dq - c - 32) >= W) p1[r] = NEG;
;     }
; }
; template <int VB>
; __device__ __forceinline__ void pv_tile(f32x16* o, int vb0, bf16x8 pa0, bf16x8 pa1, bf16x8 pa2, bf16x8 pa3) {
;     ...
;     PV_D0(0); PV_D0(1); PV_D0(2); PV_D0(3);
.LBB0_97:
	ds_read_b64_tr_b16 v[172:173], v185 offset:0x4000
	ds_read_b64_tr_b16 v[174:175], v185 offset:0x4800
	ds_read_b64_tr_b16 v[206:207], v185 offset:0x5000
	ds_read_b64_tr_b16 v[208:209], v185 offset:0x5800
	ds_read_b64_tr_b16 v[224:225], v185 offset:0x6000
	ds_read_b64_tr_b16 v[226:227], v185 offset:0x6800
	ds_read_b64_tr_b16 v[228:229], v185 offset:0x7000
	ds_read_b64_tr_b16 v[230:231], v185 offset:0x7800
	s_waitcnt lgkmcnt(0)
	s_nop 0
	v_mfma_f32_32x32x16_bf16 v[50:65], v[148:151], v[172:175], v[50:65]
	ds_read_b64_tr_b16 v[172:173], v185 offset:0x4200
	ds_read_b64_tr_b16 v[174:175], v185 offset:0x4a00
	v_mfma_f32_32x32x16_bf16 v[50:65], v[152:155], v[206:209], v[50:65]
	ds_read_b64_tr_b16 v[206:207], v185 offset:0x5200
	ds_read_b64_tr_b16 v[208:209], v185 offset:0x5a00
	v_mfma_f32_32x32x16_bf16 v[50:65], v[156:159], v[224:227], v[50:65]
	ds_read_b64_tr_b16 v[224:225], v185 offset:0x6200
	ds_read_b64_tr_b16 v[226:227], v185 offset:0x6a00
	v_mfma_f32_32x32x16_bf16 v[50:65], v[160:163], v[228:231], v[50:65]
	ds_read_b64_tr_b16 v[228:229], v185 offset:0x7200
	ds_read_b64_tr_b16 v[230:231], v185 offset:0x7a00
	s_waitcnt lgkmcnt(0)
	v_mfma_f32_32x32x16_bf16 v[34:49], v[148:151], v[172:175], v[34:49]
	ds_read_b64_tr_b16 v[172:173], v185 offset:0x4400
	ds_read_b64_tr_b16 v[174:175], v185 offset:0x4c00
	v_mfma_f32_32x32x16_bf16 v[34:49], v[152:155], v[206:209], v[34:49]
	ds_read_b64_tr_b16 v[206:207], v185 offset:0x5400
	ds_read_b64_tr_b16 v[208:209], v185 offset:0x5c00
	v_mfma_f32_32x32x16_bf16 v[34:49], v[156:159], v[224:227], v[34:49]
	ds_read_b64_tr_b16 v[224:225], v185 offset:0x6400
	ds_read_b64_tr_b16 v[226:227], v185 offset:0x6c00
	v_mfma_f32_32x32x16_bf16 v[34:49], v[160:163], v[228:231], v[34:49]
	ds_read_b64_tr_b16 v[228:229], v185 offset:0x7400
	ds_read_b64_tr_b16 v[230:231], v185 offset:0x7c00
	s_waitcnt lgkmcnt(0)
	v_mfma_f32_32x32x16_bf16 v[18:33], v[148:151], v[172:175], v[18:33]
	ds_read_b64_tr_b16 v[172:173], v185 offset:0x4600
	ds_read_b64_tr_b16 v[174:175], v185 offset:0x4e00
	v_mfma_f32_32x32x16_bf16 v[18:33], v[152:155], v[206:209], v[18:33]
	ds_read_b64_tr_b16 v[206:207], v185 offset:0x5600
	ds_read_b64_tr_b16 v[208:209], v185 offset:0x5e00
	v_mfma_f32_32x32x16_bf16 v[18:33], v[156:159], v[224:227], v[18:33]
	ds_read_b64_tr_b16 v[224:225], v185 offset:0x6600
	ds_read_b64_tr_b16 v[226:227], v185 offset:0x6e00
	v_mfma_f32_32x32x16_bf16 v[18:33], v[160:163], v[228:231], v[18:33]
	ds_read_b64_tr_b16 v[228:229], v185 offset:0x7600
	ds_read_b64_tr_b16 v[230:231], v185 offset:0x7e00
	s_waitcnt lgkmcnt(0)
	v_mfma_f32_32x32x16_bf16 v[2:17], v[148:151], v[172:175], v[2:17]
	s_add_i32 s0, s7, 64
	s_cmp_le_i32 s0, s6
	v_mfma_f32_32x32x16_bf16 v[2:17], v[152:155], v[206:209], v[2:17]
	v_mfma_f32_32x32x16_bf16 v[2:17], v[156:159], v[224:227], v[2:17]
	v_mfma_f32_32x32x16_bf16 v[2:17], v[160:163], v[228:231], v[2:17]
	s_mov_b64 vcc, s[22:23]
	s_cbranch_vccz .Lmy_hs2_nok
	s_waitcnt vmcnt(1)
	ds_write_b128 v188, v[140:143] offset:49152
	s_waitcnt vmcnt(0)
	ds_write_b128 v188, v[144:147] offset:57344
.Lmy_hs2_nok:
	s_cbranch_scc1 .LBB0_99
	v_add_u32_e32 v148, 0x4000003b, v197
	v_cmp_gt_u32_e32 vcc, 2.0, v148
	v_add_u32_e32 v148, 27, v197
	s_nop 0
	v_cndmask_b32_e32 v82, v220, v82, vcc
	v_cmp_lt_u32_e32 vcc, s33, v148
	v_add_u32_e32 v148, 58, v197
	s_nop 0
	v_cndmask_b32_e32 v66, v220, v66, vcc
	v_cmp_lt_u32_e32 vcc, s33, v148
	v_add_u32_e32 v148, 26, v197
	s_nop 0
	v_cndmask_b32_e32 v83, v220, v83, vcc
	v_cmp_lt_u32_e32 vcc, s33, v148
	v_add_u32_e32 v148, 57, v197
	s_nop 0
	v_cndmask_b32_e32 v67, v220, v67, vcc
	v_cmp_lt_u32_e32 vcc, s33, v148
	v_add_u32_e32 v148, 25, v197
	s_nop 0
	v_cndmask_b32_e32 v84, v220, v84, vcc
	v_cmp_lt_u32_e32 vcc, s33, v148
	v_add_u32_e32 v148, 56, v197
	s_nop 0
	v_cndmask_b32_e32 v68, v220, v68, vcc
	v_cmp_lt_u32_e32 vcc, s33, v148
	v_add_u32_e32 v148, 24, v197
	s_nop 0
	v_cndmask_b32_e32 v85, v220, v85, vcc
	v_cmp_lt_u32_e32 vcc, s33, v148
	v_add_u32_e32 v148, 51, v197
	s_nop 0
	v_cndmask_b32_e32 v69, v220, v69, vcc
	v_cmp_lt_u32_e32 vcc, s33, v148
	v_add_u32_e32 v148, 19, v197
	s_nop 0
	v_cndmask_b32_e32 v86, v220, v86, vcc
	v_cmp_lt_u32_e32 vcc, s33, v148
	v_add_u32_e32 v148, 50, v197
	s_nop 0
	v_cndmask_b32_e32 v70, v220, v70, vcc
	v_cmp_lt_u32_e32 vcc, s33, v148
	v_add_u32_e32 v148, 18, v197
	s_nop 0
	v_cndmask_b32_e32 v87, v220, v87, vcc
	v_cmp_lt_u32_e32 vcc, s33, v148
	v_add_u32_e32 v148, 49, v197
	s_nop 0
	v_cndmask_b32_e32 v71, v220, v71, vcc
	v_cmp_lt_u32_e32 vcc, s33, v148
	v_add_u32_e32 v148, 17, v197
	s_nop 0
	v_cndmask_b32_e32 v88, v220, v88, vcc
	v_cmp_lt_u32_e32 vcc, s33, v148
	v_add_u32_e32 v148, 48, v197
	s_nop 0
	v_cndmask_b32_e32 v72, v220, v72, vcc
	v_cmp_lt_u32_e32 vcc, s33, v148
	v_add_u32_e32 v148, 16, v197
	s_nop 0
	v_cndmask_b32_e32 v89, v220, v89, vcc
	v_cmp_lt_u32_e32 vcc, s33, v148
	v_add_u32_e32 v148, 43, v197
	s_nop 0
	v_cndmask_b32_e32 v73, v220, v73, vcc
	v_cmp_lt_u32_e32 vcc, s33, v148
	v_add_u32_e32 v148, 11, v197
	s_nop 0
	v_cndmask_b32_e32 v90, v220, v90, vcc
	v_cmp_lt_u32_e32 vcc, s33, v148
	v_add_u32_e32 v148, 42, v197
	s_nop 0
	v_cndmask_b32_e32 v74, v220, v74, vcc
	v_cmp_lt_u32_e32 vcc, s33, v148
	v_add_u32_e32 v148, 10, v197
	s_nop 0
	v_cndmask_b32_e32 v91, v220, v91, vcc
	v_cmp_lt_u32_e32 vcc, s33, v148
	v_add_u32_e32 v148, 41, v197
	s_nop 0
	v_cndmask_b32_e32 v75, v220, v75, vcc
	v_cmp_lt_u32_e32 vcc, s33, v148
	v_add_u32_e32 v148, 9, v197
	s_nop 0
	v_cndmask_b32_e32 v92, v220, v92, vcc
	v_cmp_lt_u32_e32 vcc, s33, v148
	v_add_u32_e32 v148, 40, v197
	s_nop 0
	v_cndmask_b32_e32 v76, v220, v76, vcc
	v_cmp_lt_u32_e32 vcc, s33, v148
	v_add_u32_e32 v148, 8, v197
	s_nop 0
	v_cndmask_b32_e32 v93, v220, v93, vcc
	v_cmp_lt_u32_e32 vcc, s33, v148
	v_add_u32_e32 v148, 35, v197
	s_nop 0
	v_cndmask_b32_e32 v77, v220, v77, vcc
	v_cmp_lt_u32_e32 vcc, s33, v148
	v_add_u32_e32 v148, 3, v197
	s_nop 0
	v_cndmask_b32_e32 v94, v220, v94, vcc
	v_cmp_lt_u32_e32 vcc, s33, v148
	v_add_u32_e32 v148, 34, v197
	s_nop 0
	v_cndmask_b32_e32 v78, v220, v78, vcc
	v_cmp_lt_u32_e32 vcc, s33, v148
	v_add_u32_e32 v148, 2, v197
	s_nop 0
	v_cndmask_b32_e32 v95, v220, v95, vcc
	v_cmp_lt_u32_e32 vcc, s33, v148
	v_add_u32_e32 v148, 33, v197
	s_nop 0
	v_cndmask_b32_e32 v79, v220, v79, vcc
	v_cmp_lt_u32_e32 vcc, s33, v148
	v_add_u32_e32 v148, 1, v197
	s_nop 0
	v_cndmask_b32_e32 v96, v220, v96, vcc
	v_cmp_lt_u32_e32 vcc, s33, v148
	v_add_u32_e32 v148, 32, v197
	s_nop 0
	v_cndmask_b32_e32 v80, v220, v80, vcc
	v_cmp_lt_u32_e32 vcc, s33, v148
	s_nop 1
	v_cndmask_b32_e32 v97, v220, v97, vcc
	v_cmp_lt_u32_e32 vcc, s33, v197
	s_nop 1
	v_cndmask_b32_e32 v81, v220, v81, vcc
; __device__ __forceinline__ void partialSM(f32x16& p0, f32x16& p1, float& m_reg, float& mn, float& alpha, bool rs) {
;     float pmax = p0[0]; for (int r = 1; r < 16; ++r) pmax = fmaxf(pmax, p0[r]); for (int r = 0; r < 16; ++r) pmax = fmaxf(pmax, p1[r]);
;     if (!rs) pmax = -__builtin_inff();
;     { auto rr = __builtin_amdgcn_permlane32_swap(__float_as_uint(pmax), __float_as_uint(pmax), false, false);
;       pmax = fmaxf(__uint_as_float(rr[0]), __uint_as_float(rr[1])); }
;     constexpr float C2 = 1.4426950408889634f * SCALE;
;     if (__builtin_expect(__all((pmax - m_reg) * SCALE <= THR), 1)) { mn = m_reg; alpha = 1.f; }
;     else { mn = fmaxf(m_reg, pmax); alpha = __builtin_amdgcn_exp2f((m_reg - mn) * C2); m_reg = mn; }
.LBB0_99:
	s_add_i32 s0, s3, -1
	s_lshr_b32 s8, s0, 2
	s_cmp_ge_i32 s8, s44
	s_cselect_b64 s[0:1], -1, 0
	s_lshl_b32 s8, 1, s8
	v_and_b32_e32 v148, s8, v165
	v_cmp_ne_u32_e32 vcc, 0, v148
	v_max_f32_e32 v148, v83, v83
	v_max_f32_e32 v149, v82, v82
	v_max_f32_e32 v148, v149, v148
	v_max3_f32 v148, v148, v84, v85
	v_max3_f32 v148, v148, v86, v87
	v_max3_f32 v148, v148, v88, v89
	v_max3_f32 v148, v148, v90, v91
	v_max3_f32 v148, v148, v92, v93
	v_max3_f32 v148, v148, v94, v95
	v_max3_f32 v148, v148, v96, v97
	v_max3_f32 v148, v148, v66, v67
	v_max3_f32 v148, v148, v68, v69
	v_max3_f32 v148, v148, v70, v71
	v_max3_f32 v148, v148, v72, v73
	v_max3_f32 v148, v148, v74, v75
	v_max3_f32 v148, v148, v76, v77
	v_max3_f32 v148, v148, v78, v79
	v_max3_f32 v148, v148, v80, v81
	s_or_b64 s[40:41], s[0:1], vcc
	v_cndmask_b32_e64 v148, v220, v148, s[40:41]
	v_mov_b32_e32 v149, v148
	s_nop 1
	v_permlane32_swap_b32_e32 v148, v149
	v_max_f32_e32 v149, v149, v149
	v_max_f32_e32 v148, v148, v148
	v_max_f32_e32 v148, v148, v149
	v_sub_f32_e32 v149, v148, v179
	v_mul_f32_e32 v149, 0x3db504f3, v149
	v_cmp_ge_f32_e32 vcc, s91, v149
	s_cmp_eq_u64 vcc, exec
	s_cselect_b64 s[42:43], -1, 0
	s_andn2_b64 vcc, exec, s[22:23]
	s_cbranch_vccnz .LBB0_101
	s_waitcnt vmcnt(0)
.LBB0_101:
	s_waitcnt vmcnt(3)
	v_max_f32_e32 v100, v179, v179
	v_max_f32_e32 v100, v100, v148
	v_sub_f32_e32 v101, v179, v100
	v_mul_f32_e32 v101, 0x3e0293ee, v101
	v_exp_f32_e32 v101, v101
	s_nop 0
	v_cndmask_b32_e64 v201, v101, 1.0, s[42:43]
	v_cmp_gt_f32_e32 vcc, 1.0, v201
	s_cbranch_vccz .LBB0_105
	s_and_saveexec_b64 s[0:1], s[38:39]
	ds_write_b32 v187, v201 offset:128
	s_or_b64 exec, exec, s[0:1]
	s_waitcnt lgkmcnt(0)
	s_waitcnt vmcnt(2)
	ds_read_b128 v[136:139], v186 offset:224
	s_waitcnt vmcnt(1)
	ds_read_b128 v[140:143], v186 offset:192
	s_waitcnt vmcnt(0)
	ds_read_b128 v[144:147], v186 offset:160
	ds_read_b128 v[148:151], v186 offset:128
	s_waitcnt lgkmcnt(3)
	v_pk_mul_f32 v[64:65], v[64:65], v[138:139]
	s_waitcnt lgkmcnt(2)
	v_pk_mul_f32 v[60:61], v[60:61], v[142:143]
	s_waitcnt lgkmcnt(1)
	v_pk_mul_f32 v[56:57], v[56:57], v[146:147]
	s_waitcnt lgkmcnt(0)
	v_pk_mul_f32 v[52:53], v[52:53], v[150:151]
	v_pk_mul_f32 v[62:63], v[62:63], v[136:137]
	v_pk_mul_f32 v[58:59], v[58:59], v[140:141]
	v_pk_mul_f32 v[54:55], v[54:55], v[144:145]
	v_pk_mul_f32 v[50:51], v[50:51], v[148:149]
	v_pk_mul_f32 v[48:49], v[48:49], v[138:139]
	v_pk_mul_f32 v[44:45], v[44:45], v[142:143]
	v_pk_mul_f32 v[40:41], v[40:41], v[146:147]
	v_pk_mul_f32 v[36:37], v[36:37], v[150:151]
	v_pk_mul_f32 v[46:47], v[46:47], v[136:137]
	v_pk_mul_f32 v[42:43], v[42:43], v[140:141]
	v_pk_mul_f32 v[38:39], v[38:39], v[144:145]
	v_pk_mul_f32 v[34:35], v[34:35], v[148:149]
	v_pk_mul_f32 v[32:33], v[32:33], v[138:139]
	v_pk_mul_f32 v[28:29], v[28:29], v[142:143]
	v_pk_mul_f32 v[24:25], v[24:25], v[146:147]
	v_pk_mul_f32 v[20:21], v[20:21], v[150:151]
	v_pk_mul_f32 v[30:31], v[30:31], v[136:137]
	v_pk_mul_f32 v[26:27], v[26:27], v[140:141]
	v_pk_mul_f32 v[22:23], v[22:23], v[144:145]
	v_pk_mul_f32 v[18:19], v[18:19], v[148:149]
	v_pk_mul_f32 v[16:17], v[16:17], v[138:139]
	v_pk_mul_f32 v[12:13], v[12:13], v[142:143]
	v_pk_mul_f32 v[8:9], v[8:9], v[146:147]
	v_pk_mul_f32 v[4:5], v[4:5], v[150:151]
	v_pk_mul_f32 v[14:15], v[14:15], v[136:137]
	v_pk_mul_f32 v[10:11], v[10:11], v[140:141]
	v_pk_mul_f32 v[6:7], v[6:7], v[144:145]
	v_pk_mul_f32 v[2:3], v[2:3], v[148:149]
